# EpiFinalGate: 16 serialized stash loads hoisted to block start (on top of v17)
# speedup vs baseline: 1.0063x; 1.0039x over previous
; DI unsigned pack2(float a, float b) { f2_t v = {a, b}; bf2_t r = __builtin_convertvector(v, bf2_t); return __builtin_bit_cast(unsigned, r); }
; DI void unpack8(const u32x4& v, f32x4& lo, f32x4& hi) { lo = f32x4{bflo(v[0]), bfhi(v[0]), bflo(v[1]), bfhi(v[1])}; hi = f32x4{bflo(v[2]), bfhi(v[2]), bflo(v[3]), bfhi(v[3])}; }
; template <class Epi>
; DI void apply_epi_staged(WVP char* smem, AccT& acc, int bc0, const Epi& epi) {
;     ...
;   for (int bj = 0; bj < 2; ++bj) for (int m = 0; m < 4; ++m) {
;     for (int n = 0; n < 2; ++n) {
;       const int rl = wr2 * 64 + m * 16 + fq2 * 4, tc = bj * HALF + wc2 * 32 + n * 16 + fr2;
;       f32x4 r0, r1;
;       epi.tr(acc[0][bj][m][n], acc[1][bj][m][n], rl, bc0 + tc, bj * 8 + m * 2 + n, t2, r0, r1);
;       uint2 v0; v0.x = pack2(r0[0], r0[1]); v0.y = pack2(r0[2], r0[3]);
;       *(uint2*)(smem + tc * PITCH + rl * 2) = v0;
;       if (NC == 256) { uint2 v1; v1.x = pack2(r1[0], r1[1]); v1.y = pack2(r1[2], r1[3]); *(uint2*)(smem + tc * PITCH + (HALF + rl) * 2) = v1; }
;   DI void tr(const f32x4& a0, const f32x4& a1, int, int, int j, int tid, f32x4& r0, f32x4& r1) const {
;     const u32x4 vc = *(const u32x4*)stash_ptr(mg + nbase, DM, bc0, j, tid);
;     f32x4 c0, c1; unpack8(vc, c0, c1); r0 = a0 * c0; r1 = a1 * c1; }
.LBB0_207:
	v_mbcnt_lo_u32_b32 v230, -1, 0
	v_mbcnt_hi_u32_b32 v230, -1, v230
	v_add_u32_e32 v231, s3, v230
	v_lshlrev_b32_e32 v230, 4, v230
	v_ashrrev_i32_e32 v231, 5, v231
	v_and_b32_e32 v230, 0x1f0, v230
	v_add_u32_e32 v231, s12, v231
	v_lshl_add_u32 v230, v231, 11, v230
	global_load_dwordx4 v[152:155], v230, s[14:15]
	v_add_u32_e32 v230, 0x8000, v230
	global_load_dwordx4 v[156:159], v230, s[14:15]
	v_add_u32_e32 v230, 0x8000, v230
	global_load_dwordx4 v[160:163], v230, s[14:15]
	v_add_u32_e32 v230, 0x8000, v230
	global_load_dwordx4 v[164:167], v230, s[14:15]
	v_add_u32_e32 v230, 0x8000, v230
	global_load_dwordx4 v[168:171], v230, s[14:15]
	v_add_u32_e32 v230, 0x8000, v230
	global_load_dwordx4 v[172:175], v230, s[14:15]
	v_add_u32_e32 v230, 0x8000, v230
	global_load_dwordx4 v[176:179], v230, s[14:15]
	v_add_u32_e32 v230, 0x8000, v230
	global_load_dwordx4 v[180:183], v230, s[14:15]
	v_add_u32_e32 v230, 0x8000, v230
	global_load_dwordx4 v[184:187], v230, s[14:15]
	v_add_u32_e32 v230, 0x8000, v230
	global_load_dwordx4 v[188:191], v230, s[14:15]
	v_add_u32_e32 v230, 0x8000, v230
	global_load_dwordx4 v[192:195], v230, s[14:15]
	v_add_u32_e32 v230, 0x8000, v230
	global_load_dwordx4 v[196:199], v230, s[14:15]
	v_add_u32_e32 v230, 0x8000, v230
	global_load_dwordx4 v[200:203], v230, s[14:15]
	v_add_u32_e32 v230, 0x8000, v230
	global_load_dwordx4 v[206:209], v230, s[14:15]
	v_add_u32_e32 v230, 0x8000, v230
	global_load_dwordx4 v[210:213], v230, s[14:15]
	v_add_u32_e32 v230, 0x8000, v230
	global_load_dwordx4 v[214:217], v230, s[14:15]
	v_mbcnt_lo_u32_b32 v0, -1, 0
	v_mbcnt_hi_u32_b32 v0, -1, v0
	s_nop 0
	v_add_u32_e32 v130, s3, v0
	v_ashrrev_i32_e32 v132, 5, v130
	v_readfirstlane_b32 s0, v130
	s_ashr_i32 s0, s0, 1
	v_add_u32_e32 v132, s12, v132
	s_and_b32 s1, s0, 0x60
	v_ashrrev_i32_e32 v133, 31, v132
	v_and_or_b32 v140, v0, 15, s1
	v_lshrrev_b32_e32 v131, 1, v0
	v_lshlrev_b64 v[132:133], 11, v[132:133]
	v_lshlrev_b32_e32 v0, 4, v0
	v_lshl_add_u64 v[132:133], s[14:15], 0, v[132:133]
	v_and_b32_e32 v0, 0x1f0, v0
	v_lshl_add_u64 v[132:133], v[132:133], 0, v[0:1]
	s_and_b32 s0, s0, 0xffffff80
	v_and_or_b32 v131, v131, 24, s0
	s_movk_i32 s0, 0x210
	s_waitcnt vmcnt(15)
	v_lshlrev_b32_e32 v136, 16, v152
	v_and_b32_e32 v137, 0xffff0000, v152
	v_lshlrev_b32_e32 v132, 16, v153
	v_and_b32_e32 v133, 0xffff0000, v153
	v_lshlrev_b32_e32 v138, 16, v154
	v_and_b32_e32 v139, 0xffff0000, v154
	v_lshlrev_b32_e32 v134, 16, v155
	v_and_b32_e32 v135, 0xffff0000, v155
	v_pk_mul_f32 v[128:129], v[128:129], v[132:133]
	v_pk_mul_f32 v[132:133], v[124:125], v[134:135]
	v_pk_mul_f32 v[134:135], v[122:123], v[138:139]
	v_add_u32_e32 v122, 0x200, v130
	v_pk_mul_f32 v[126:127], v[126:127], v[136:137]
	v_ashrrev_i32_e32 v125, 5, v122
	v_cvt_pk_bf16_f32 v136, v126, v127
	v_add_u32_e32 v126, s12, v125
	v_ashrrev_i32_e32 v127, 31, v126
	v_lshlrev_b64 v[126:127], 11, v[126:127]
	v_lshl_add_u64 v[126:127], s[14:15], 0, v[126:127]
	v_lshl_add_u64 v[126:127], v[126:127], 0, v[0:1]
	v_cvt_pk_bf16_f32 v137, v128, v129
	v_cvt_pk_bf16_f32 v134, v134, v135
	v_cvt_pk_bf16_f32 v135, v132, v133
	v_mad_u32_u24 v123, v140, s0, 0
	v_add_u32_e32 v124, v123, v131
	s_waitcnt vmcnt(14)
	v_lshlrev_b32_e32 v132, 16, v156
	v_and_b32_e32 v133, 0xffff0000, v156
	v_lshlrev_b32_e32 v126, 16, v157
	v_and_b32_e32 v127, 0xffff0000, v157
	v_lshlrev_b32_e32 v138, 16, v158
	v_and_b32_e32 v139, 0xffff0000, v158
	v_lshlrev_b32_e32 v128, 16, v159
	v_and_b32_e32 v129, 0xffff0000, v159
	v_pk_mul_f32 v[118:119], v[118:119], v[132:133]
	v_pk_mul_f32 v[120:121], v[120:121], v[126:127]
	v_pk_mul_f32 v[126:127], v[116:117], v[128:129]
	v_cvt_pk_bf16_f32 v116, v118, v119
	v_add_u32_e32 v118, 0x400, v130
	v_cvt_pk_bf16_f32 v117, v120, v121
	v_ashrrev_i32_e32 v120, 5, v118
	v_add_u32_e32 v120, s12, v120
	v_ashrrev_i32_e32 v121, 31, v120
	v_lshlrev_b64 v[120:121], 11, v[120:121]
	v_lshl_add_u64 v[120:121], s[14:15], 0, v[120:121]
	v_pk_mul_f32 v[114:115], v[114:115], v[138:139]
	v_lshl_add_u64 v[120:121], v[120:121], 0, v[0:1]
	v_cvt_pk_bf16_f32 v114, v114, v115
	v_cvt_pk_bf16_f32 v115, v126, v127
	v_or_b32_e32 v119, 32, v131
	s_waitcnt vmcnt(13)
	v_lshlrev_b32_e32 v132, 16, v162
	v_and_b32_e32 v133, 0xffff0000, v162
	v_lshlrev_b32_e32 v128, 16, v163
	v_and_b32_e32 v129, 0xffff0000, v163
	v_pk_mul_f32 v[108:109], v[108:109], v[128:129]
	v_pk_mul_f32 v[106:107], v[106:107], v[132:133]
	v_lshlrev_b32_e32 v120, 16, v160
	v_cvt_pk_bf16_f32 v106, v106, v107
	v_cvt_pk_bf16_f32 v107, v108, v109
	ds_write2_b64 v124, v[134:135], v[106:107] offset0:32 offset1:36
	v_add_u32_e32 v106, 0x600, v130
	v_ashrrev_i32_e32 v107, 5, v106
	v_add_u32_e32 v108, s12, v107
	v_ashrrev_i32_e32 v109, 31, v108
	v_and_b32_e32 v121, 0xffff0000, v160
	v_lshlrev_b32_e32 v126, 16, v161
	v_and_b32_e32 v127, 0xffff0000, v161
	v_lshlrev_b64 v[108:109], 11, v[108:109]
	v_pk_mul_f32 v[112:113], v[112:113], v[126:127]
	v_pk_mul_f32 v[110:111], v[110:111], v[120:121]
	v_lshl_add_u64 v[108:109], s[14:15], 0, v[108:109]
	v_cvt_pk_bf16_f32 v110, v110, v111
	v_cvt_pk_bf16_f32 v111, v112, v113
	v_lshl_add_u64 v[108:109], v[108:109], 0, v[0:1]
	ds_write2_b64 v124, v[136:137], v[110:111] offset1:4
	s_waitcnt vmcnt(12)
; DI unsigned pack2(float a, float b) { f2_t v = {a, b}; bf2_t r = __builtin_convertvector(v, bf2_t); return __builtin_bit_cast(unsigned, r); }
; DI void unpack8(const u32x4& v, f32x4& lo, f32x4& hi) { lo = f32x4{bflo(v[0]), bfhi(v[0]), bflo(v[1]), bfhi(v[1])}; hi = f32x4{bflo(v[2]), bfhi(v[2]), bflo(v[3]), bfhi(v[3])}; }
; template <class Epi>
; DI void apply_epi_staged(WVP char* smem, AccT& acc, int bc0, const Epi& epi) {
;     ...
;   for (int bj = 0; bj < 2; ++bj) for (int m = 0; m < 4; ++m) {
;     for (int n = 0; n < 2; ++n) {
;       const int rl = wr2 * 64 + m * 16 + fq2 * 4, tc = bj * HALF + wc2 * 32 + n * 16 + fr2;
;       f32x4 r0, r1;
;       epi.tr(acc[0][bj][m][n], acc[1][bj][m][n], rl, bc0 + tc, bj * 8 + m * 2 + n, t2, r0, r1);
;       uint2 v0; v0.x = pack2(r0[0], r0[1]); v0.y = pack2(r0[2], r0[3]);
;       *(uint2*)(smem + tc * PITCH + rl * 2) = v0;
;       if (NC == 256) { uint2 v1; v1.x = pack2(r1[0], r1[1]); v1.y = pack2(r1[2], r1[3]); *(uint2*)(smem + tc * PITCH + (HALF + rl) * 2) = v1; }
;   DI void tr(const f32x4& a0, const f32x4& a1, int, int, int j, int tid, f32x4& r0, f32x4& r1) const {
;     const u32x4 vc = *(const u32x4*)stash_ptr(mg + nbase, DM, bc0, j, tid);
;     f32x4 c0, c1; unpack8(vc, c0, c1); r0 = a0 * c0; r1 = a1 * c1; }
	v_lshlrev_b32_e32 v112, 16, v164
	v_and_b32_e32 v113, 0xffff0000, v164
	v_lshlrev_b32_e32 v108, 16, v165
	v_and_b32_e32 v109, 0xffff0000, v165
	v_lshlrev_b32_e32 v120, 16, v166
	v_and_b32_e32 v121, 0xffff0000, v166
	v_lshlrev_b32_e32 v110, 16, v167
	v_and_b32_e32 v111, 0xffff0000, v167
	v_pk_mul_f32 v[104:105], v[104:105], v[108:109]
	v_pk_mul_f32 v[102:103], v[102:103], v[112:113]
	v_pk_mul_f32 v[108:109], v[96:97], v[110:111]
	v_pk_mul_f32 v[94:95], v[94:95], v[120:121]
	v_cvt_pk_bf16_f32 v102, v102, v103
	v_cvt_pk_bf16_f32 v103, v104, v105
	v_add_u32_e32 v96, 0x2000, v124
	v_cvt_pk_bf16_f32 v94, v94, v95
	v_cvt_pk_bf16_f32 v95, v108, v109
	ds_write2_b64 v96, v[116:117], v[102:103] offset0:32 offset1:36
	ds_write2_b64 v96, v[114:115], v[94:95] offset0:64 offset1:68
	v_add_u32_e32 v94, 0x800, v130
	v_ashrrev_i32_e32 v97, 5, v94
	v_add_u32_e32 v102, s12, v97
	v_ashrrev_i32_e32 v103, 31, v102
	v_lshlrev_b64 v[102:103], 11, v[102:103]
	v_lshl_add_u64 v[102:103], s[14:15], 0, v[102:103]
	v_lshl_add_u64 v[102:103], v[102:103], 0, v[0:1]
	v_or_b32_e32 v95, 64, v131
	s_waitcnt vmcnt(11)
	v_lshlrev_b32_e32 v110, 16, v170
	v_and_b32_e32 v111, 0xffff0000, v170
	v_lshlrev_b32_e32 v104, 16, v171
	v_and_b32_e32 v105, 0xffff0000, v171
	v_pk_mul_f32 v[90:91], v[90:91], v[110:111]
	v_pk_mul_f32 v[92:93], v[92:93], v[104:105]
	v_cvt_pk_bf16_f32 v104, v90, v91
	v_add_u32_e32 v90, 0xa00, v130
	v_ashrrev_i32_e32 v91, 5, v90
	v_cvt_pk_bf16_f32 v105, v92, v93
	v_add_u32_e32 v92, s12, v91
	v_ashrrev_i32_e32 v93, 31, v92
	v_lshlrev_b64 v[92:93], 11, v[92:93]
	v_lshlrev_b32_e32 v108, 16, v168
	v_and_b32_e32 v109, 0xffff0000, v168
	v_lshlrev_b32_e32 v102, 16, v169
	v_and_b32_e32 v103, 0xffff0000, v169
	v_lshl_add_u64 v[92:93], s[14:15], 0, v[92:93]
	v_pk_mul_f32 v[100:101], v[100:101], v[102:103]
	v_pk_mul_f32 v[98:99], v[98:99], v[108:109]
	v_lshl_add_u64 v[92:93], v[92:93], 0, v[0:1]
	v_cvt_pk_bf16_f32 v102, v98, v99
	v_cvt_pk_bf16_f32 v103, v100, v101
	s_waitcnt vmcnt(10)
	v_lshlrev_b32_e32 v92, 16, v172
	v_and_b32_e32 v93, 0xffff0000, v172
	v_lshlrev_b32_e32 v98, 16, v173
	v_and_b32_e32 v99, 0xffff0000, v173
	v_lshlrev_b32_e32 v108, 16, v174
	v_and_b32_e32 v109, 0xffff0000, v174
	v_lshlrev_b32_e32 v100, 16, v175
	v_and_b32_e32 v101, 0xffff0000, v175
	v_pk_mul_f32 v[86:87], v[86:87], v[92:93]
	v_pk_mul_f32 v[88:89], v[88:89], v[98:99]
	v_pk_mul_f32 v[92:93], v[84:85], v[100:101]
	v_cvt_pk_bf16_f32 v84, v86, v87
	v_add_u32_e32 v86, 0xc00, v130
	v_cvt_pk_bf16_f32 v85, v88, v89
	v_ashrrev_i32_e32 v88, 5, v86
	v_add_u32_e32 v88, s12, v88
	v_ashrrev_i32_e32 v89, 31, v88
	v_lshlrev_b64 v[88:89], 11, v[88:89]
	v_lshl_add_u64 v[88:89], s[14:15], 0, v[88:89]
	v_lshl_add_u64 v[88:89], v[88:89], 0, v[0:1]
	v_pk_mul_f32 v[82:83], v[82:83], v[108:109]
	v_or_b32_e32 v87, 0x60, v131
	v_cvt_pk_bf16_f32 v82, v82, v83
	v_cvt_pk_bf16_f32 v83, v92, v93
	s_waitcnt vmcnt(9)
	v_lshlrev_b32_e32 v88, 16, v176
	v_and_b32_e32 v89, 0xffff0000, v176
	v_lshlrev_b32_e32 v92, 16, v177
	v_and_b32_e32 v93, 0xffff0000, v177
	v_lshlrev_b32_e32 v98, 16, v178
	v_and_b32_e32 v99, 0xffff0000, v178
	v_lshlrev_b32_e32 v100, 16, v179
	v_and_b32_e32 v101, 0xffff0000, v179
	v_pk_mul_f32 v[76:77], v[76:77], v[100:101]
	v_pk_mul_f32 v[74:75], v[74:75], v[98:99]
	v_pk_mul_f32 v[80:81], v[80:81], v[92:93]
	v_cvt_pk_bf16_f32 v74, v74, v75
	v_cvt_pk_bf16_f32 v75, v76, v77
	ds_write2_b64 v124, v[104:105], v[74:75] offset0:40 offset1:44
	v_add_u32_e32 v74, 0xe00, v130
	v_ashrrev_i32_e32 v75, 5, v74
	v_add_u32_e32 v76, s12, v75
	v_ashrrev_i32_e32 v77, 31, v76
	v_lshlrev_b64 v[76:77], 11, v[76:77]
	v_pk_mul_f32 v[78:79], v[78:79], v[88:89]
	v_lshl_add_u64 v[76:77], s[14:15], 0, v[76:77]
	v_cvt_pk_bf16_f32 v78, v78, v79
	v_cvt_pk_bf16_f32 v79, v80, v81
	v_lshl_add_u64 v[76:77], v[76:77], 0, v[0:1]
	ds_write2_b64 v124, v[102:103], v[78:79] offset0:8 offset1:12
	s_waitcnt vmcnt(8)
	v_lshlrev_b32_e32 v80, 16, v180
	v_and_b32_e32 v81, 0xffff0000, v180
	v_lshlrev_b32_e32 v76, 16, v181
	v_and_b32_e32 v77, 0xffff0000, v181
	v_lshlrev_b32_e32 v88, 16, v182
	v_and_b32_e32 v89, 0xffff0000, v182
	v_lshlrev_b32_e32 v78, 16, v183
	v_and_b32_e32 v79, 0xffff0000, v183
	v_pk_mul_f32 v[72:73], v[72:73], v[76:77]
	v_pk_mul_f32 v[70:71], v[70:71], v[80:81]
	v_pk_mul_f32 v[64:65], v[64:65], v[78:79]
	v_pk_mul_f32 v[62:63], v[62:63], v[88:89]
	v_cvt_pk_bf16_f32 v70, v70, v71
	v_cvt_pk_bf16_f32 v71, v72, v73
	v_cvt_pk_bf16_f32 v62, v62, v63
	v_cvt_pk_bf16_f32 v63, v64, v65
	ds_write2_b64 v96, v[84:85], v[70:71] offset0:40 offset1:44
	ds_write2_b64 v96, v[82:83], v[62:63] offset0:72 offset1:76
	v_add_u32_e32 v62, 0x1000, v130
	v_ashrrev_i32_e32 v63, 5, v62
	v_add_u32_e32 v64, s12, v63
	v_ashrrev_i32_e32 v65, 31, v64
	v_lshlrev_b64 v[64:65], 11, v[64:65]
	v_lshl_add_u64 v[64:65], s[14:15], 0, v[64:65]
	v_lshl_add_u64 v[64:65], v[64:65], 0, v[0:1]
	s_waitcnt vmcnt(7)
	v_lshlrev_b32_e32 v64, 16, v184
	v_and_b32_e32 v65, 0xffff0000, v184
	v_lshlrev_b32_e32 v70, 16, v185
	v_and_b32_e32 v71, 0xffff0000, v185
	v_lshlrev_b32_e32 v76, 16, v186
	v_and_b32_e32 v77, 0xffff0000, v186
	v_lshlrev_b32_e32 v72, 16, v187
	v_and_b32_e32 v73, 0xffff0000, v187
	v_pk_mul_f32 v[68:69], v[68:69], v[70:71]
	v_pk_mul_f32 v[64:65], v[66:67], v[64:65]
	v_pk_mul_f32 v[60:61], v[60:61], v[72:73]
	v_pk_mul_f32 v[66:67], v[58:59], v[76:77]
	v_add_u32_e32 v59, 0x10800, v123
	v_cvt_pk_bf16_f32 v64, v64, v65
	v_cvt_pk_bf16_f32 v65, v68, v69
	v_add_u32_e32 v58, v59, v131
	v_cvt_pk_bf16_f32 v66, v66, v67
	v_cvt_pk_bf16_f32 v67, v60, v61
	ds_write2_b64 v58, v[64:65], v[66:67] offset1:32
	v_add_u32_e32 v58, 0x1200, v130
	v_ashrrev_i32_e32 v60, 5, v58
	v_add_u32_e32 v60, s12, v60
	v_ashrrev_i32_e32 v61, 31, v60
	v_lshlrev_b64 v[60:61], 11, v[60:61]
	v_lshl_add_u64 v[60:61], s[14:15], 0, v[60:61]
	v_lshl_add_u64 v[60:61], v[60:61], 0, v[0:1]
	s_waitcnt vmcnt(6)
; DI unsigned pack2(float a, float b) { f2_t v = {a, b}; bf2_t r = __builtin_convertvector(v, bf2_t); return __builtin_bit_cast(unsigned, r); }
; DI void unpack8(const u32x4& v, f32x4& lo, f32x4& hi) { lo = f32x4{bflo(v[0]), bfhi(v[0]), bflo(v[1]), bfhi(v[1])}; hi = f32x4{bflo(v[2]), bfhi(v[2]), bflo(v[3]), bfhi(v[3])}; }
; template <class Epi>
; DI void apply_epi_staged(WVP char* smem, AccT& acc, int bc0, const Epi& epi) {
;     ...
;   for (int bj = 0; bj < 2; ++bj) for (int m = 0; m < 4; ++m) {
;     for (int n = 0; n < 2; ++n) {
;       const int rl = wr2 * 64 + m * 16 + fq2 * 4, tc = bj * HALF + wc2 * 32 + n * 16 + fr2;
;       f32x4 r0, r1;
;       epi.tr(acc[0][bj][m][n], acc[1][bj][m][n], rl, bc0 + tc, bj * 8 + m * 2 + n, t2, r0, r1);
;       uint2 v0; v0.x = pack2(r0[0], r0[1]); v0.y = pack2(r0[2], r0[3]);
;       *(uint2*)(smem + tc * PITCH + rl * 2) = v0;
;       if (NC == 256) { uint2 v1; v1.x = pack2(r1[0], r1[1]); v1.y = pack2(r1[2], r1[3]); *(uint2*)(smem + tc * PITCH + (HALF + rl) * 2) = v1; }
;   DI void tr(const f32x4& a0, const f32x4& a1, int, int, int j, int tid, f32x4& r0, f32x4& r1) const {
;     const u32x4 vc = *(const u32x4*)stash_ptr(mg + nbase, DM, bc0, j, tid);
;     f32x4 c0, c1; unpack8(vc, c0, c1); r0 = a0 * c0; r1 = a1 * c1; }
	v_lshlrev_b32_e32 v60, 16, v188
	v_and_b32_e32 v61, 0xffff0000, v188
	v_lshlrev_b32_e32 v64, 16, v189
	v_and_b32_e32 v65, 0xffff0000, v189
	v_lshlrev_b32_e32 v68, 16, v190
	v_and_b32_e32 v69, 0xffff0000, v190
	v_lshlrev_b32_e32 v66, 16, v191
	v_and_b32_e32 v67, 0xffff0000, v191
	v_pk_mul_f32 v[56:57], v[56:57], v[64:65]
	v_pk_mul_f32 v[54:55], v[54:55], v[60:61]
	v_pk_mul_f32 v[52:53], v[52:53], v[66:67]
	v_pk_mul_f32 v[60:61], v[50:51], v[68:69]
	v_add_u32_e32 v51, 0x12900, v123
	v_cvt_pk_bf16_f32 v54, v54, v55
	v_cvt_pk_bf16_f32 v55, v56, v57
	v_add_u32_e32 v50, v51, v131
	v_cvt_pk_bf16_f32 v56, v60, v61
	v_cvt_pk_bf16_f32 v57, v52, v53
	ds_write2_b64 v50, v[54:55], v[56:57] offset1:32
	v_add_u32_e32 v50, 0x1400, v130
	v_ashrrev_i32_e32 v52, 5, v50
	v_add_u32_e32 v52, s12, v52
	v_ashrrev_i32_e32 v53, 31, v52
	v_lshlrev_b64 v[52:53], 11, v[52:53]
	v_lshl_add_u64 v[52:53], s[14:15], 0, v[52:53]
	v_lshl_add_u64 v[52:53], v[52:53], 0, v[0:1]
	s_waitcnt vmcnt(5)
	v_lshlrev_b32_e32 v56, 16, v192
	v_and_b32_e32 v57, 0xffff0000, v192
	v_lshlrev_b32_e32 v52, 16, v193
	v_and_b32_e32 v53, 0xffff0000, v193
	v_lshlrev_b32_e32 v60, 16, v194
	v_and_b32_e32 v61, 0xffff0000, v194
	v_lshlrev_b32_e32 v54, 16, v195
	v_and_b32_e32 v55, 0xffff0000, v195
	v_pk_mul_f32 v[48:49], v[48:49], v[52:53]
	v_pk_mul_f32 v[46:47], v[46:47], v[56:57]
	v_pk_mul_f32 v[44:45], v[44:45], v[54:55]
	v_pk_mul_f32 v[42:43], v[42:43], v[60:61]
	v_cvt_pk_bf16_f32 v46, v46, v47
	v_cvt_pk_bf16_f32 v47, v48, v49
	v_add_u32_e32 v48, v59, v119
	v_cvt_pk_bf16_f32 v42, v42, v43
	v_cvt_pk_bf16_f32 v43, v44, v45
	ds_write2_b64 v48, v[46:47], v[42:43] offset1:32
	v_add_u32_e32 v42, 0x1600, v130
	v_ashrrev_i32_e32 v43, 5, v42
	v_add_u32_e32 v44, s12, v43
	v_ashrrev_i32_e32 v45, 31, v44
	v_lshlrev_b64 v[44:45], 11, v[44:45]
	v_lshl_add_u64 v[44:45], s[14:15], 0, v[44:45]
	v_lshl_add_u64 v[44:45], v[44:45], 0, v[0:1]
	s_waitcnt vmcnt(4)
	v_lshlrev_b32_e32 v48, 16, v196
	v_and_b32_e32 v49, 0xffff0000, v196
	v_lshlrev_b32_e32 v44, 16, v197
	v_and_b32_e32 v45, 0xffff0000, v197
	v_lshlrev_b32_e32 v52, 16, v198
	v_and_b32_e32 v53, 0xffff0000, v198
	v_lshlrev_b32_e32 v46, 16, v199
	v_and_b32_e32 v47, 0xffff0000, v199
	v_pk_mul_f32 v[40:41], v[40:41], v[44:45]
	v_pk_mul_f32 v[38:39], v[38:39], v[48:49]
	v_pk_mul_f32 v[32:33], v[32:33], v[46:47]
	v_pk_mul_f32 v[30:31], v[30:31], v[52:53]
	v_cvt_pk_bf16_f32 v38, v38, v39
	v_cvt_pk_bf16_f32 v39, v40, v41
	v_add_u32_e32 v40, v51, v119
	v_cvt_pk_bf16_f32 v30, v30, v31
	v_cvt_pk_bf16_f32 v31, v32, v33
	ds_write2_b64 v40, v[38:39], v[30:31] offset1:32
	v_add_u32_e32 v30, 0x1800, v130
	v_ashrrev_i32_e32 v31, 5, v30
	v_add_u32_e32 v32, s12, v31
	v_ashrrev_i32_e32 v33, 31, v32
	v_lshlrev_b64 v[32:33], 11, v[32:33]
	v_lshl_add_u64 v[32:33], s[14:15], 0, v[32:33]
	v_lshl_add_u64 v[32:33], v[32:33], 0, v[0:1]
	v_add_u32_e32 v31, v59, v95
	s_waitcnt vmcnt(3)
	v_lshlrev_b32_e32 v32, 16, v200
	v_and_b32_e32 v33, 0xffff0000, v200
	v_lshlrev_b32_e32 v38, 16, v201
	v_and_b32_e32 v39, 0xffff0000, v201
	v_lshlrev_b32_e32 v44, 16, v202
	v_and_b32_e32 v45, 0xffff0000, v202
	v_lshlrev_b32_e32 v40, 16, v203
	v_and_b32_e32 v41, 0xffff0000, v203
	v_pk_mul_f32 v[36:37], v[36:37], v[38:39]
	v_pk_mul_f32 v[32:33], v[34:35], v[32:33]
	v_pk_mul_f32 v[28:29], v[28:29], v[40:41]
	v_pk_mul_f32 v[26:27], v[26:27], v[44:45]
	v_cvt_pk_bf16_f32 v32, v32, v33
	v_cvt_pk_bf16_f32 v33, v36, v37
	v_cvt_pk_bf16_f32 v26, v26, v27
	v_cvt_pk_bf16_f32 v27, v28, v29
	ds_write2_b64 v31, v[32:33], v[26:27] offset1:32
	v_add_u32_e32 v26, 0x1a00, v130
	v_ashrrev_i32_e32 v27, 5, v26
	v_add_u32_e32 v28, s12, v27
	v_ashrrev_i32_e32 v29, 31, v28
	v_lshlrev_b64 v[28:29], 11, v[28:29]
	v_lshl_add_u64 v[28:29], s[14:15], 0, v[28:29]
	v_lshl_add_u64 v[28:29], v[28:29], 0, v[0:1]
	s_waitcnt vmcnt(2)
	v_lshlrev_b32_e32 v28, 16, v206
	v_and_b32_e32 v29, 0xffff0000, v206
	v_lshlrev_b32_e32 v32, 16, v207
	v_and_b32_e32 v33, 0xffff0000, v207
	v_lshlrev_b32_e32 v36, 16, v208
	v_and_b32_e32 v37, 0xffff0000, v208
	v_lshlrev_b32_e32 v34, 16, v209
	v_and_b32_e32 v35, 0xffff0000, v209
	v_pk_mul_f32 v[24:25], v[24:25], v[32:33]
	v_pk_mul_f32 v[22:23], v[22:23], v[28:29]
	v_pk_mul_f32 v[20:21], v[20:21], v[34:35]
	v_pk_mul_f32 v[18:19], v[18:19], v[36:37]
	v_cvt_pk_bf16_f32 v22, v22, v23
	v_cvt_pk_bf16_f32 v23, v24, v25
	v_add_u32_e32 v24, v51, v95
	v_cvt_pk_bf16_f32 v18, v18, v19
	v_cvt_pk_bf16_f32 v19, v20, v21
	ds_write2_b64 v24, v[22:23], v[18:19] offset1:32
	v_add_u32_e32 v18, 0x1c00, v130
	v_ashrrev_i32_e32 v19, 5, v18
	v_add_u32_e32 v20, s12, v19
	v_ashrrev_i32_e32 v21, 31, v20
	v_lshlrev_b64 v[20:21], 11, v[20:21]
	v_lshl_add_u64 v[20:21], s[14:15], 0, v[20:21]
	v_lshl_add_u64 v[20:21], v[20:21], 0, v[0:1]
	s_waitcnt vmcnt(1)
	v_lshlrev_b32_e32 v24, 16, v210
	v_and_b32_e32 v25, 0xffff0000, v210
	v_lshlrev_b32_e32 v20, 16, v211
	v_and_b32_e32 v21, 0xffff0000, v211
	v_lshlrev_b32_e32 v28, 16, v212
	v_and_b32_e32 v29, 0xffff0000, v212
	v_lshlrev_b32_e32 v22, 16, v213
	v_and_b32_e32 v23, 0xffff0000, v213
	v_pk_mul_f32 v[16:17], v[16:17], v[20:21]
	v_pk_mul_f32 v[14:15], v[14:15], v[24:25]
	v_pk_mul_f32 v[12:13], v[12:13], v[22:23]
	v_pk_mul_f32 v[10:11], v[10:11], v[28:29]
	v_cvt_pk_bf16_f32 v14, v14, v15
	v_cvt_pk_bf16_f32 v15, v16, v17
	v_add_u32_e32 v16, v59, v87
	v_cvt_pk_bf16_f32 v10, v10, v11
	v_cvt_pk_bf16_f32 v11, v12, v13
	ds_write2_b64 v16, v[14:15], v[10:11] offset1:32
	v_add_u32_e32 v10, 0x1e00, v130
	v_ashrrev_i32_e32 v11, 5, v10
	v_add_u32_e32 v12, s12, v11
	v_ashrrev_i32_e32 v13, 31, v12
	v_lshlrev_b64 v[12:13], 11, v[12:13]
	v_lshl_add_u64 v[12:13], s[14:15], 0, v[12:13]
	v_lshl_add_u64 v[12:13], v[12:13], 0, v[0:1]
	v_add_u32_e32 v0, v51, v87
	s_waitcnt vmcnt(0)
	v_lshlrev_b32_e32 v16, 16, v214
	v_and_b32_e32 v17, 0xffff0000, v214
	v_lshlrev_b32_e32 v12, 16, v215
	v_and_b32_e32 v13, 0xffff0000, v215
	v_lshlrev_b32_e32 v20, 16, v216
	v_and_b32_e32 v21, 0xffff0000, v216
	v_lshlrev_b32_e32 v14, 16, v217
	v_and_b32_e32 v15, 0xffff0000, v217
	v_pk_mul_f32 v[8:9], v[8:9], v[12:13]
	v_pk_mul_f32 v[6:7], v[6:7], v[16:17]
	v_pk_mul_f32 v[4:5], v[4:5], v[14:15]
	v_pk_mul_f32 v[2:3], v[2:3], v[20:21]
	v_cvt_pk_bf16_f32 v6, v6, v7
	v_cvt_pk_bf16_f32 v7, v8, v9
	v_cvt_pk_bf16_f32 v2, v2, v3
	v_cvt_pk_bf16_f32 v3, v4, v5
	ds_write2_b64 v0, v[6:7], v[2:3] offset1:32
	v_ashrrev_i32_e32 v0, 31, v130
	v_lshrrev_b32_e32 v0, 27, v0
	v_add_u32_e32 v0, v130, v0
	v_ashrrev_i32_e32 v6, 5, v0
	v_and_b32_e32 v0, 0xffffffe0, v0
	v_sub_u32_e32 v0, v130, v0
	v_mul_lo_u32 v2, v6, s0
	v_lshlrev_b32_e32 v3, 4, v0
	v_add3_u32 v2, 0, v2, v3
	v_add_u32_e32 v6, s12, v6
	s_waitcnt lgkmcnt(0)
	s_barrier
; template <class Epi>
; DI void apply_epi_staged(WVP char* smem, AccT& acc, int bc0, const Epi& epi) {
;     ...
;   constexpr int CPR = NC / 8;
; #pragma unroll
;   for (int i = 0; i < 256 * CPR / NTHR; ++i) {
;     const int L = i * NTHR + t2, row = L / CPR, ch = L % CPR;
;     const u32x4 v = *(const u32x4*)(smem + row * PITCH + ch * 16);
;     *(u32x4*)(epi.out(bc0 + row, ch)) = v;
	ds_read_b128 v[2:5], v2
	v_ashrrev_i32_e32 v7, 31, v6
	v_lshlrev_b64 v[6:7], 11, v[6:7]
	v_lshl_add_u64 v[6:7], s[10:11], 0, v[6:7]
	v_lshlrev_b32_e32 v8, 3, v0
	v_ashrrev_i32_e32 v0, 31, v122
	v_lshl_add_u64 v[6:7], v[6:7], 0, s[8:9]
	v_ashrrev_i32_e32 v9, 31, v8
	v_lshrrev_b32_e32 v0, 27, v0
	v_lshl_add_u64 v[6:7], v[8:9], 1, v[6:7]
	v_add_u32_e32 v0, v122, v0
	s_waitcnt lgkmcnt(0)
	global_store_dwordx4 v[6:7], v[2:5], off
	v_ashrrev_i32_e32 v6, 5, v0
	v_and_b32_e32 v0, 0xffffffe0, v0
	v_sub_u32_e32 v0, v122, v0
	v_mul_lo_u32 v2, v6, s0
	v_lshlrev_b32_e32 v3, 4, v0
	v_add3_u32 v2, 0, v2, v3
	v_add_u32_e32 v6, s12, v6
	ds_read_b128 v[2:5], v2
	v_ashrrev_i32_e32 v7, 31, v6
	v_lshlrev_b64 v[6:7], 11, v[6:7]
	v_lshl_add_u64 v[6:7], s[10:11], 0, v[6:7]
	v_lshlrev_b32_e32 v8, 3, v0
	v_ashrrev_i32_e32 v0, 31, v118
	v_lshl_add_u64 v[6:7], v[6:7], 0, s[8:9]
	v_ashrrev_i32_e32 v9, 31, v8
	v_lshrrev_b32_e32 v0, 27, v0
	v_lshl_add_u64 v[6:7], v[8:9], 1, v[6:7]
	v_add_u32_e32 v0, v118, v0
	s_waitcnt lgkmcnt(0)
	global_store_dwordx4 v[6:7], v[2:5], off
	v_ashrrev_i32_e32 v6, 5, v0
	v_and_b32_e32 v0, 0xffffffe0, v0
	v_sub_u32_e32 v0, v118, v0
	v_mul_lo_u32 v2, v6, s0
	v_lshlrev_b32_e32 v3, 4, v0
	v_add3_u32 v2, 0, v2, v3
	v_add_u32_e32 v6, s12, v6
	ds_read_b128 v[2:5], v2
	v_ashrrev_i32_e32 v7, 31, v6
	v_lshlrev_b64 v[6:7], 11, v[6:7]
	v_lshl_add_u64 v[6:7], s[10:11], 0, v[6:7]
	v_lshlrev_b32_e32 v8, 3, v0
	v_ashrrev_i32_e32 v0, 31, v106
	v_lshl_add_u64 v[6:7], v[6:7], 0, s[8:9]
	v_ashrrev_i32_e32 v9, 31, v8
	v_lshrrev_b32_e32 v0, 27, v0
	v_lshl_add_u64 v[6:7], v[8:9], 1, v[6:7]
	v_add_u32_e32 v0, v106, v0
	s_waitcnt lgkmcnt(0)
	global_store_dwordx4 v[6:7], v[2:5], off
	v_ashrrev_i32_e32 v6, 5, v0
	v_and_b32_e32 v0, 0xffffffe0, v0
	v_sub_u32_e32 v0, v106, v0
	v_mul_lo_u32 v2, v6, s0
	v_lshlrev_b32_e32 v3, 4, v0
	v_add3_u32 v2, 0, v2, v3
	v_add_u32_e32 v6, s12, v6
	ds_read_b128 v[2:5], v2
	v_ashrrev_i32_e32 v7, 31, v6
	v_lshlrev_b64 v[6:7], 11, v[6:7]
	v_lshl_add_u64 v[6:7], s[10:11], 0, v[6:7]
	v_lshlrev_b32_e32 v8, 3, v0
	v_ashrrev_i32_e32 v0, 31, v94
	v_lshl_add_u64 v[6:7], v[6:7], 0, s[8:9]
	v_ashrrev_i32_e32 v9, 31, v8
	v_lshrrev_b32_e32 v0, 27, v0
	v_lshl_add_u64 v[6:7], v[8:9], 1, v[6:7]
	v_add_u32_e32 v0, v94, v0
	s_waitcnt lgkmcnt(0)
	global_store_dwordx4 v[6:7], v[2:5], off
	v_ashrrev_i32_e32 v6, 5, v0
	v_and_b32_e32 v0, 0xffffffe0, v0
	v_sub_u32_e32 v0, v94, v0
	v_mul_lo_u32 v2, v6, s0
	v_lshlrev_b32_e32 v3, 4, v0
	v_add3_u32 v2, 0, v2, v3
	v_add_u32_e32 v6, s12, v6
	ds_read_b128 v[2:5], v2
	v_ashrrev_i32_e32 v7, 31, v6
	v_lshlrev_b64 v[6:7], 11, v[6:7]
	v_lshl_add_u64 v[6:7], s[10:11], 0, v[6:7]
	v_lshlrev_b32_e32 v8, 3, v0
	v_ashrrev_i32_e32 v0, 31, v90
	v_lshl_add_u64 v[6:7], v[6:7], 0, s[8:9]
	v_ashrrev_i32_e32 v9, 31, v8
	v_lshrrev_b32_e32 v0, 27, v0
	v_lshl_add_u64 v[6:7], v[8:9], 1, v[6:7]
	v_add_u32_e32 v0, v90, v0
	s_waitcnt lgkmcnt(0)
	global_store_dwordx4 v[6:7], v[2:5], off
	v_ashrrev_i32_e32 v6, 5, v0
	v_and_b32_e32 v0, 0xffffffe0, v0
	v_sub_u32_e32 v0, v90, v0
	v_mul_lo_u32 v2, v6, s0
	v_lshlrev_b32_e32 v3, 4, v0
	v_add3_u32 v2, 0, v2, v3
	v_add_u32_e32 v6, s12, v6
	ds_read_b128 v[2:5], v2
	v_ashrrev_i32_e32 v7, 31, v6
	v_lshlrev_b64 v[6:7], 11, v[6:7]
	v_lshl_add_u64 v[6:7], s[10:11], 0, v[6:7]
	v_lshlrev_b32_e32 v8, 3, v0
	v_ashrrev_i32_e32 v0, 31, v86
	v_lshl_add_u64 v[6:7], v[6:7], 0, s[8:9]
	v_ashrrev_i32_e32 v9, 31, v8
	v_lshrrev_b32_e32 v0, 27, v0
	v_lshl_add_u64 v[6:7], v[8:9], 1, v[6:7]
	v_add_u32_e32 v0, v86, v0
	s_waitcnt lgkmcnt(0)
	global_store_dwordx4 v[6:7], v[2:5], off
	v_ashrrev_i32_e32 v6, 5, v0
	v_and_b32_e32 v0, 0xffffffe0, v0
	v_sub_u32_e32 v0, v86, v0
	v_mul_lo_u32 v2, v6, s0
	v_lshlrev_b32_e32 v3, 4, v0
	v_add3_u32 v2, 0, v2, v3
	v_add_u32_e32 v6, s12, v6
	ds_read_b128 v[2:5], v2
	v_ashrrev_i32_e32 v7, 31, v6
	v_lshlrev_b64 v[6:7], 11, v[6:7]
	v_lshl_add_u64 v[6:7], s[10:11], 0, v[6:7]
	v_lshlrev_b32_e32 v8, 3, v0
	v_ashrrev_i32_e32 v0, 31, v74
	v_lshl_add_u64 v[6:7], v[6:7], 0, s[8:9]
	v_ashrrev_i32_e32 v9, 31, v8
	v_lshrrev_b32_e32 v0, 27, v0
	v_lshl_add_u64 v[6:7], v[8:9], 1, v[6:7]
	v_add_u32_e32 v0, v74, v0
	s_waitcnt lgkmcnt(0)
	global_store_dwordx4 v[6:7], v[2:5], off
	v_ashrrev_i32_e32 v6, 5, v0
	v_and_b32_e32 v0, 0xffffffe0, v0
	v_sub_u32_e32 v0, v74, v0
	v_mul_lo_u32 v2, v6, s0
	v_lshlrev_b32_e32 v3, 4, v0
	v_add3_u32 v2, 0, v2, v3
	v_add_u32_e32 v6, s12, v6
	ds_read_b128 v[2:5], v2
	v_ashrrev_i32_e32 v7, 31, v6
	v_lshlrev_b64 v[6:7], 11, v[6:7]
	v_lshl_add_u64 v[6:7], s[10:11], 0, v[6:7]
	v_lshlrev_b32_e32 v8, 3, v0
	v_ashrrev_i32_e32 v0, 31, v62
	v_lshl_add_u64 v[6:7], v[6:7], 0, s[8:9]
	v_ashrrev_i32_e32 v9, 31, v8
	v_lshrrev_b32_e32 v0, 27, v0
	v_lshl_add_u64 v[6:7], v[8:9], 1, v[6:7]
	v_add_u32_e32 v0, v62, v0
	s_waitcnt lgkmcnt(0)
; template <class Epi>
; DI void apply_epi_staged(WVP char* smem, AccT& acc, int bc0, const Epi& epi) {
;     ...
;   constexpr int CPR = NC / 8;
; #pragma unroll
;   for (int i = 0; i < 256 * CPR / NTHR; ++i) {
;     const int L = i * NTHR + t2, row = L / CPR, ch = L % CPR;
;     const u32x4 v = *(const u32x4*)(smem + row * PITCH + ch * 16);
;     *(u32x4*)(epi.out(bc0 + row, ch)) = v;
; __global__ void __launch_bounds__(NTHR) mega(Params p) {
;     ...
;         for (int id = BID; id < nwg; id += G) {
	global_store_dwordx4 v[6:7], v[2:5], off
	v_ashrrev_i32_e32 v6, 5, v0
	v_and_b32_e32 v0, 0xffffffe0, v0
	v_sub_u32_e32 v0, v62, v0
	v_mul_lo_u32 v2, v6, s0
	v_lshlrev_b32_e32 v3, 4, v0
	v_add3_u32 v2, 0, v2, v3
	v_add_u32_e32 v6, s12, v6
	ds_read_b128 v[2:5], v2
	v_ashrrev_i32_e32 v7, 31, v6
	v_lshlrev_b64 v[6:7], 11, v[6:7]
	v_lshl_add_u64 v[6:7], s[10:11], 0, v[6:7]
	v_lshlrev_b32_e32 v8, 3, v0
	v_ashrrev_i32_e32 v0, 31, v58
	v_lshl_add_u64 v[6:7], v[6:7], 0, s[8:9]
	v_ashrrev_i32_e32 v9, 31, v8
	v_lshrrev_b32_e32 v0, 27, v0
	v_lshl_add_u64 v[6:7], v[8:9], 1, v[6:7]
	v_add_u32_e32 v0, v58, v0
	s_waitcnt lgkmcnt(0)
	global_store_dwordx4 v[6:7], v[2:5], off
	v_ashrrev_i32_e32 v6, 5, v0
	v_and_b32_e32 v0, 0xffffffe0, v0
	v_sub_u32_e32 v0, v58, v0
	v_mul_lo_u32 v2, v6, s0
	v_lshlrev_b32_e32 v3, 4, v0
	v_add3_u32 v2, 0, v2, v3
	v_add_u32_e32 v6, s12, v6
	ds_read_b128 v[2:5], v2
	v_ashrrev_i32_e32 v7, 31, v6
	v_lshlrev_b64 v[6:7], 11, v[6:7]
	v_lshl_add_u64 v[6:7], s[10:11], 0, v[6:7]
	v_lshlrev_b32_e32 v8, 3, v0
	v_ashrrev_i32_e32 v0, 31, v50
	v_lshl_add_u64 v[6:7], v[6:7], 0, s[8:9]
	v_ashrrev_i32_e32 v9, 31, v8
	v_lshrrev_b32_e32 v0, 27, v0
	v_lshl_add_u64 v[6:7], v[8:9], 1, v[6:7]
	v_add_u32_e32 v0, v50, v0
	s_waitcnt lgkmcnt(0)
	global_store_dwordx4 v[6:7], v[2:5], off
	v_ashrrev_i32_e32 v6, 5, v0
	v_and_b32_e32 v0, 0xffffffe0, v0
	v_sub_u32_e32 v0, v50, v0
	v_mul_lo_u32 v2, v6, s0
	v_lshlrev_b32_e32 v3, 4, v0
	v_add3_u32 v2, 0, v2, v3
	v_add_u32_e32 v6, s12, v6
	ds_read_b128 v[2:5], v2
	v_ashrrev_i32_e32 v7, 31, v6
	v_lshlrev_b64 v[6:7], 11, v[6:7]
	v_lshl_add_u64 v[6:7], s[10:11], 0, v[6:7]
	v_lshlrev_b32_e32 v8, 3, v0
	v_ashrrev_i32_e32 v0, 31, v42
	v_lshl_add_u64 v[6:7], v[6:7], 0, s[8:9]
	v_ashrrev_i32_e32 v9, 31, v8
	v_lshrrev_b32_e32 v0, 27, v0
	v_lshl_add_u64 v[6:7], v[8:9], 1, v[6:7]
	v_add_u32_e32 v0, v42, v0
	s_waitcnt lgkmcnt(0)
	global_store_dwordx4 v[6:7], v[2:5], off
	v_ashrrev_i32_e32 v6, 5, v0
	v_and_b32_e32 v0, 0xffffffe0, v0
	v_sub_u32_e32 v0, v42, v0
	v_mul_lo_u32 v2, v6, s0
	v_lshlrev_b32_e32 v3, 4, v0
	v_add3_u32 v2, 0, v2, v3
	v_add_u32_e32 v6, s12, v6
	ds_read_b128 v[2:5], v2
	v_ashrrev_i32_e32 v7, 31, v6
	v_lshlrev_b64 v[6:7], 11, v[6:7]
	v_lshl_add_u64 v[6:7], s[10:11], 0, v[6:7]
	v_lshlrev_b32_e32 v8, 3, v0
	v_ashrrev_i32_e32 v0, 31, v30
	v_lshl_add_u64 v[6:7], v[6:7], 0, s[8:9]
	v_ashrrev_i32_e32 v9, 31, v8
	v_lshrrev_b32_e32 v0, 27, v0
	v_lshl_add_u64 v[6:7], v[8:9], 1, v[6:7]
	v_add_u32_e32 v0, v30, v0
	s_waitcnt lgkmcnt(0)
	global_store_dwordx4 v[6:7], v[2:5], off
	v_ashrrev_i32_e32 v6, 5, v0
	v_and_b32_e32 v0, 0xffffffe0, v0
	v_sub_u32_e32 v0, v30, v0
	v_mul_lo_u32 v2, v6, s0
	v_lshlrev_b32_e32 v3, 4, v0
	v_add3_u32 v2, 0, v2, v3
	v_add_u32_e32 v6, s12, v6
	ds_read_b128 v[2:5], v2
	v_ashrrev_i32_e32 v7, 31, v6
	v_lshlrev_b64 v[6:7], 11, v[6:7]
	v_lshl_add_u64 v[6:7], s[10:11], 0, v[6:7]
	v_lshlrev_b32_e32 v8, 3, v0
	v_ashrrev_i32_e32 v0, 31, v26
	v_lshl_add_u64 v[6:7], v[6:7], 0, s[8:9]
	v_ashrrev_i32_e32 v9, 31, v8
	v_lshrrev_b32_e32 v0, 27, v0
	v_lshl_add_u64 v[6:7], v[8:9], 1, v[6:7]
	v_add_u32_e32 v0, v26, v0
	s_waitcnt lgkmcnt(0)
	global_store_dwordx4 v[6:7], v[2:5], off
	v_ashrrev_i32_e32 v6, 5, v0
	v_and_b32_e32 v0, 0xffffffe0, v0
	v_sub_u32_e32 v0, v26, v0
	v_mul_lo_u32 v2, v6, s0
	v_lshlrev_b32_e32 v3, 4, v0
	v_add3_u32 v2, 0, v2, v3
	v_add_u32_e32 v6, s12, v6
	ds_read_b128 v[2:5], v2
	v_ashrrev_i32_e32 v7, 31, v6
	v_lshlrev_b64 v[6:7], 11, v[6:7]
	v_lshl_add_u64 v[6:7], s[10:11], 0, v[6:7]
	v_lshlrev_b32_e32 v8, 3, v0
	v_ashrrev_i32_e32 v0, 31, v18
	v_lshl_add_u64 v[6:7], v[6:7], 0, s[8:9]
	v_ashrrev_i32_e32 v9, 31, v8
	v_lshrrev_b32_e32 v0, 27, v0
	v_lshl_add_u64 v[6:7], v[8:9], 1, v[6:7]
	v_add_u32_e32 v0, v18, v0
	s_waitcnt lgkmcnt(0)
	global_store_dwordx4 v[6:7], v[2:5], off
	v_ashrrev_i32_e32 v6, 5, v0
	v_and_b32_e32 v0, 0xffffffe0, v0
	v_sub_u32_e32 v0, v18, v0
	v_mul_lo_u32 v2, v6, s0
	v_lshlrev_b32_e32 v3, 4, v0
	v_add3_u32 v2, 0, v2, v3
	v_add_u32_e32 v6, s12, v6
	ds_read_b128 v[2:5], v2
	v_ashrrev_i32_e32 v7, 31, v6
	v_lshlrev_b64 v[6:7], 11, v[6:7]
	v_lshl_add_u64 v[6:7], s[10:11], 0, v[6:7]
	v_lshlrev_b32_e32 v8, 3, v0
	v_ashrrev_i32_e32 v0, 31, v10
	v_lshl_add_u64 v[6:7], v[6:7], 0, s[8:9]
	v_ashrrev_i32_e32 v9, 31, v8
	v_lshrrev_b32_e32 v0, 27, v0
	v_lshl_add_u64 v[6:7], v[8:9], 1, v[6:7]
	v_add_u32_e32 v0, v10, v0
	s_waitcnt lgkmcnt(0)
	global_store_dwordx4 v[6:7], v[2:5], off
	v_ashrrev_i32_e32 v6, 5, v0
	v_and_b32_e32 v0, 0xffffffe0, v0
	v_sub_u32_e32 v0, v10, v0
	v_mul_lo_u32 v2, v6, s0
	v_lshlrev_b32_e32 v3, 4, v0
	v_add3_u32 v2, 0, v2, v3
	v_add_u32_e32 v6, s12, v6
	ds_read_b128 v[2:5], v2
	v_ashrrev_i32_e32 v7, 31, v6
	v_lshlrev_b64 v[6:7], 11, v[6:7]
	v_lshl_add_u64 v[6:7], s[10:11], 0, v[6:7]
	v_lshlrev_b32_e32 v8, 3, v0
	v_readlane_b32 s0, v255, 21
	v_lshl_add_u64 v[6:7], v[6:7], 0, s[8:9]
	v_ashrrev_i32_e32 v9, 31, v8
	s_add_i32 s51, s51, s0
	v_lshl_add_u64 v[6:7], v[8:9], 1, v[6:7]
	s_cmpk_gt_i32 s51, 0x1ff
	s_waitcnt lgkmcnt(0)
	global_store_dwordx4 v[6:7], v[2:5], off
	s_cbranch_scc1 .LBB0_258
